# attention interior loop: next tile's K fragments read during the softmax/PV section into spare VGPRs (no K-read burst before QK), tile DMA waited one iteration after issue (vmcnt(0)), DMA issue code i
# speedup vs baseline: 1.0031x; 1.0031x over previous
.LBB0_104:
	s_mov_b32 s43, s13
	s_mul_i32 s52, s43, 0x3000
	s_add_i32 s52, s52, 16
	v_add_u32_e32 v174, s52, v149
	ds_read_b128 v[204:207], v174
	ds_read_b128 v[208:211], v174 offset:32
	ds_read_b128 v[212:215], v174 offset:6144
	ds_read_b128 v[216:219], v174 offset:6176
	ds_read_b128 v[220:223], v174 offset:64
	ds_read_b128 v[224:227], v174 offset:96
	ds_read_b128 v[228:231], v174 offset:6208
	ds_read_b128 v[232:235], v174 offset:6240
	v_add_u32_e32 v175, s52, v150
	ds_read_b128 v[176:179], v175
	ds_read_b128 v[180:183], v175 offset:6144
	v_add_u32_e32 v174, s52, v151
	ds_read_b128 v[184:187], v174
	ds_read_b128 v[188:191], v174 offset:6144
.Lattn_rot:
	s_waitcnt lgkmcnt(0)
	v_mfma_f32_32x32x16_bf16 v[48:63], v[204:207], v[82:85], 0
	v_mfma_f32_32x32x16_bf16 v[64:79], v[212:215], v[82:85], 0
	s_add_i32 s4, s49, 2
	s_cmp_lt_u32 s4, s36
	s_cselect_b32 s4, s4, s48
	s_mul_i32 s14, s4, 0x3000
	s_mul_hi_u32 s15, s4, 0x3000
	s_add_u32 s14, s6, s14
	s_mul_i32 s52, s37, 0x3000
	s_addc_u32 s15, s7, s15
	s_add_i32 s52, s33, s52
	v_lshl_add_u64 v[172:173], v[144:145], 1, s[14:15]
	s_mov_b32 m0, s52
	s_andn2_b64 vcc, exec, s[10:11]
	global_load_lds_dwordx4 v[172:173], off
	v_mfma_f32_32x32x16_bf16 v[48:63], v[208:211], v[86:89], v[48:63]
	v_mfma_f32_32x32x16_bf16 v[64:79], v[216:219], v[86:89], v[64:79]
	s_cbranch_vccnz .LBB0_106
	v_lshl_add_u64 v[172:173], v[80:81], 1, s[14:15]
	s_add_i32 m0, s52, 0x2000
	s_nop 0
	global_load_lds_dwordx4 v[172:173], off
.LBB0_106:
	v_mfma_f32_32x32x16_bf16 v[48:63], v[220:223], v[90:93], v[48:63]
	v_mfma_f32_32x32x16_bf16 v[64:79], v[228:231], v[90:93], v[64:79]
	s_lshl_b64 s[14:15], s[4:5], 17
	s_lshl_b32 s4, s37, 13
	v_lshl_add_u64 v[172:173], v[146:147], 0, s[14:15]
	s_add_i32 s4, s33, s4
	v_lshl_add_u64 v[172:173], v[172:173], 0, s[20:21]
	s_add_i32 m0, s4, 0x9000
	global_load_lds_dwordx4 v[172:173], off
	v_mfma_f32_32x32x16_bf16 v[48:63], v[224:227], v[94:97], v[48:63]
	v_mfma_f32_32x32x16_bf16 v[64:79], v[232:235], v[94:97], v[64:79]
	v_mfma_f32_32x32x16_bf16 v[48:63], v[176:179], v[98:101], v[48:63]
	v_mfma_f32_32x32x16_bf16 v[64:79], v[180:183], v[98:101], v[64:79]
	v_mfma_f32_32x32x16_bf16 v[48:63], v[184:187], v[102:105], v[48:63]
	v_mfma_f32_32x32x16_bf16 v[64:79], v[188:191], v[102:105], v[64:79]
	v_lshl_add_u32 v108, s43, 13, v131
	ds_read_b64_tr_b16 v[132:133], v108 offset:0
	ds_read_b64_tr_b16 v[134:135], v108 offset:1024
	ds_read_b64_tr_b16 v[160:161], v108 offset:64
	ds_read_b64_tr_b16 v[162:163], v108 offset:1088
	ds_read_b64_tr_b16 v[126:127], v108 offset:2048
	ds_read_b64_tr_b16 v[128:129], v108 offset:3072
	ds_read_b64_tr_b16 v[122:123], v108 offset:2112
	ds_read_b64_tr_b16 v[124:125], v108 offset:3136
	ds_read_b64_tr_b16 v[118:119], v108 offset:4096
	ds_read_b64_tr_b16 v[120:121], v108 offset:5120
	ds_read_b64_tr_b16 v[114:115], v108 offset:4160
	ds_read_b64_tr_b16 v[116:117], v108 offset:5184
	ds_read_b64_tr_b16 v[110:111], v108 offset:6144
	ds_read_b64_tr_b16 v[112:113], v108 offset:7168
	ds_read_b64_tr_b16 v[106:107], v108 offset:6208
	ds_read_b64_tr_b16 v[108:109], v108 offset:7232
	s_mul_i32 s14, s45, 0x3000
	s_add_i32 s14, s14, 16
	v_add_u32_e32 v174, s14, v149
	s_nop 8
	v_exp_f32_e32 v50, v50
	v_exp_f32_e32 v51, v51
	v_exp_f32_e32 v52, v52
	v_exp_f32_e32 v53, v53
	v_exp_f32_e32 v54, v54
	v_exp_f32_e32 v55, v55
	v_exp_f32_e32 v48, v48
	v_exp_f32_e32 v49, v49
	v_add_f32_e32 v32, v32, v50
	v_add_f32_e32 v33, v33, v51
	v_add_f32_e32 v34, v34, v52
	v_add_f32_e32 v35, v35, v53
	v_add_f32_e32 v32, v32, v54
	v_add_f32_e32 v33, v33, v55
	v_add_f32_e32 v34, v34, v48
	v_add_f32_e32 v35, v35, v49
	s_waitcnt lgkmcnt(14)
	v_cvt_pk_bf16_f32 v48, v48, v49
	v_cvt_pk_bf16_f32 v49, v50, v51
	v_cvt_pk_bf16_f32 v50, v52, v53
	v_cvt_pk_bf16_f32 v51, v54, v55
	s_nop 1
	v_mfma_f32_32x32x16_bf16 v[0:15], v[132:135], v[48:51], v[0:15]
	ds_read_b128 v[204:207], v174
	ds_read_b128 v[208:211], v174 offset:32
	ds_read_b128 v[212:215], v174 offset:6144
	v_exp_f32_e32 v56, v56
	v_exp_f32_e32 v57, v57
	v_exp_f32_e32 v58, v58
	v_exp_f32_e32 v59, v59
	v_exp_f32_e32 v60, v60
	v_exp_f32_e32 v61, v61
	v_exp_f32_e32 v62, v62
	s_waitcnt lgkmcnt(15)
	v_mfma_f32_32x32x16_bf16 v[16:31], v[160:163], v[48:51], v[16:31]
	ds_read_b128 v[216:219], v174 offset:6176
	ds_read_b128 v[220:223], v174 offset:64
	ds_read_b128 v[224:227], v174 offset:96
	v_exp_f32_e32 v63, v63
	v_exp_f32_e32 v64, v64
	v_exp_f32_e32 v65, v65
	v_exp_f32_e32 v66, v66
	v_exp_f32_e32 v67, v67
	v_exp_f32_e32 v68, v68
	v_exp_f32_e32 v69, v69
	v_add_f32_e32 v32, v32, v56
	v_add_f32_e32 v33, v33, v57
	v_add_f32_e32 v34, v34, v58
	v_add_f32_e32 v35, v35, v59
	v_add_f32_e32 v32, v32, v60
	v_add_f32_e32 v33, v33, v61
	v_add_f32_e32 v34, v34, v62
	v_add_f32_e32 v35, v35, v63
	v_cvt_pk_bf16_f32 v48, v56, v57
	v_cvt_pk_bf16_f32 v49, v58, v59
	v_cvt_pk_bf16_f32 v50, v60, v61
	v_cvt_pk_bf16_f32 v51, v62, v63
	v_exp_f32_e32 v70, v70
	v_exp_f32_e32 v71, v71
	v_exp_f32_e32 v72, v72
	s_waitcnt lgkmcnt(15)
	v_mfma_f32_32x32x16_bf16 v[0:15], v[126:129], v[48:51], v[0:15]
	ds_read_b128 v[228:231], v174 offset:6208
	ds_read_b128 v[232:235], v174 offset:6240
	v_add_u32_e32 v175, s14, v150
	ds_read_b128 v[176:179], v175
	v_exp_f32_e32 v73, v73
	v_exp_f32_e32 v74, v74
	v_exp_f32_e32 v75, v75
	v_exp_f32_e32 v76, v76
	v_exp_f32_e32 v77, v77
	v_exp_f32_e32 v78, v78
	v_exp_f32_e32 v79, v79
	s_waitcnt lgkmcnt(15)
	v_mfma_f32_32x32x16_bf16 v[16:31], v[122:125], v[48:51], v[16:31]
	ds_read_b128 v[180:183], v175 offset:6144
	v_add_u32_e32 v174, s14, v151
	ds_read_b128 v[184:187], v174
	ds_read_b128 v[188:191], v174 offset:6144
	v_add_f32_e32 v32, v32, v64
	v_add_f32_e32 v33, v33, v65
	v_add_f32_e32 v34, v34, v66
	v_add_f32_e32 v35, v35, v67
	v_add_f32_e32 v32, v32, v68
	v_add_f32_e32 v33, v33, v69
	v_add_f32_e32 v34, v34, v70
	v_add_f32_e32 v35, v35, v71
	v_cvt_pk_bf16_f32 v48, v64, v65
	v_cvt_pk_bf16_f32 v49, v66, v67
	v_cvt_pk_bf16_f32 v50, v68, v69
	v_cvt_pk_bf16_f32 v51, v70, v71
	s_nop 0
	s_waitcnt lgkmcnt(15)
	v_mfma_f32_32x32x16_bf16 v[0:15], v[118:121], v[48:51], v[0:15]
	v_mfma_f32_32x32x16_bf16 v[16:31], v[114:117], v[48:51], v[16:31]
	v_add_f32_e32 v32, v32, v72
	v_add_f32_e32 v33, v33, v73
	v_add_f32_e32 v34, v34, v74
	v_add_f32_e32 v35, v35, v75
	v_add_f32_e32 v32, v32, v76
	v_add_f32_e32 v33, v33, v77
	v_add_f32_e32 v34, v34, v78
	v_add_f32_e32 v35, v35, v79
	v_cvt_pk_bf16_f32 v48, v72, v73
	v_cvt_pk_bf16_f32 v49, v74, v75
	v_cvt_pk_bf16_f32 v50, v76, v77
	v_cvt_pk_bf16_f32 v51, v78, v79
	s_nop 0
	s_waitcnt lgkmcnt(14)
	v_mfma_f32_32x32x16_bf16 v[0:15], v[110:113], v[48:51], v[0:15]
	s_waitcnt lgkmcnt(12)
	v_mfma_f32_32x32x16_bf16 v[16:31], v[106:109], v[48:51], v[16:31]
	s_waitcnt vmcnt(0)
	s_add_i32 s49, s49, 1
	s_cmp_eq_u32 s42, s49
	s_cselect_b32 s13, s13, s45
	s_cselect_b32 s45, s45, s37
	s_cselect_b32 s37, s37, s43
	s_cselect_b32 s43, s43, s13
	s_barrier
	s_cbranch_scc1 .LBB0_113
	s_branch .Lattn_rot
